# v13 + sample-step loops and ssd_pass2 chunk top: back-to-back single loads each behind a full vmcnt(0) drain merged under one wait (5 sites)
# speedup vs baseline: 1.0008x; 1.0008x over previous
; __device__ __forceinline__ float bf2f(bf16 v) { return __uint_as_float(((unsigned)v) << 16); }
; __device__ __forceinline__ float sigmoidf_(float x) { return frcp_(1.0f + __expf(-x)); }
; __device__ __forceinline__ float siluf_(float x) { return x * frcp_(1.0f + __expf(-x)); }
; __host__ __device__ __forceinline__ int hg_vpos(int e) { return (e & 64) + 16 * (e & 3) + ((e & 63) >> 2); }
; #define LAS __attribute__((address_space(3)))
; __device__ __forceinline__ void hgrn_sample_step(const bf16* proj, const float* lbs_l, const float* hgn_l, const float* state_in, float* state_out, bf16* ohg, int bh, int tid, LAS unsigned char* lds,
;                                                  f32x4 (&st)[8], int bh_next) {
;     const int b = bh >> 3, h = bh & 7, lane = tid & 63, w = tid >> 6;
;     LAS float* sq = (LAS float*)lds; LAS float* sg = sq + 128; LAS float* sk = sq + 256; LAS float* sv = sq + 384; LAS float* so = (LAS float*)(lds + 8192); LAS float* sred = (LAS float*)(lds + 16384);
;     const size_t row = (size_t)MP + b;
;     float ogv = 0.f, q_ = 0.f, f_ = 0.f, v_ = 0.f, lb_ = 0.f;
;     if (tid < 128) { const bf16* pr = proj + row * LDP + h * 128; q_ = bf2f(pr[PC_Q + tid]); f_ = bf2f(pr[PC_F + tid]); lb_ = lbs_l[h * 128 + tid]; v_ = bf2f(pr[PC_I + hg_vpos(tid)]); ogv = bf2f(pr[PC_OG + tid]); }
;     if (tid < 128) { const float fg = lb_ + (1.f - lb_) * sigmoidf_(f_);
;         sq[tid] = siluf_(q_) * 0.08838834764831845f; sg[tid] = fg; sk[tid] = 1.f - fg; sv[tid] = v_; }
.LBB0_408:
	s_ashr_i32 s6, s22, 3
	v_mov_b32_e32 v8, v138
	s_add_i32 s10, s6, 0x4000
	s_movk_i32 s6, 0x80
	s_and_b32 s18, s22, 7
	s_ashr_i32 s11, s10, 31
	v_cmp_gt_i32_e64 s[6:7], s6, v8
	v_bfrev_b32_e32 v38, 1
	v_mov_b32_e32 v36, 0
	v_ashrrev_i32_e32 v9, 31, v8
	v_mov_b32_e32 v68, 0
	v_mov_b32_e32 v10, 0
	v_mov_b32_e32 v37, 0
	s_and_saveexec_b64 s[8:9], s[6:7]
	s_cbranch_execz .LBB0_410
	s_mul_i32 s13, s10, 0x6200
	s_mul_hi_i32 s12, s10, 0x6200
	s_add_u32 s13, s78, s13
	s_addc_u32 s14, s79, s12
	s_lshl_b32 s12, s18, 8
	s_add_u32 s12, s13, s12
	s_addc_u32 s13, s14, 0
	v_lshl_add_u64 v[38:39], v[8:9], 1, s[12:13]
	global_load_ushort v10, v[38:39], off offset:2048
	v_lshl_add_u32 v36, s18, 7, v8
	v_ashrrev_i32_e32 v37, 31, v36
	v_lshl_add_u64 v[36:37], v[36:37], 2, s[96:97]
	global_load_dword v36, v[36:37], off
	v_lshlrev_b32_e32 v37, 4, v8
	v_and_b32_e32 v37, 48, v37
	v_bfe_u32 v40, v8, 2, 4
	s_waitcnt vmcnt(0) lgkmcnt(0)
	v_lshlrev_b32_e32 v42, 16, v10
	v_and_b32_e32 v10, 64, v8
	v_or3_b32 v10, v37, v10, v40
	v_lshlrev_b32_e32 v10, 1, v10
	v_lshl_add_u64 v[40:41], s[12:13], 0, v[10:11]
	s_movk_i32 s12, 0x1000
	v_add_co_u32_e32 v40, vcc, s12, v40
	s_nop 1
	v_addc_co_u32_e32 v41, vcc, 0, v41, vcc
	global_load_ushort v10, v[40:41], off
	global_load_ushort v37, v[38:39], off
	v_add_co_u32_e32 v38, vcc, 0x1000, v38
	s_nop 1
	v_addc_co_u32_e32 v39, vcc, 0, v39, vcc
	global_load_ushort v38, v[38:39], off offset:2048
	s_waitcnt vmcnt(0) lgkmcnt(0)
	v_lshlrev_b32_e32 v10, 16, v10
	v_lshlrev_b32_e32 v37, 16, v37
	v_lshlrev_b32_e32 v68, 16, v38
	v_mul_f32_e32 v38, 0xbfb8aa3b, v42

; __device__ __forceinline__ float bf2f(bf16 v) { return __uint_as_float(((unsigned)v) << 16); }
; __device__ __forceinline__ float siluf_(float x) { return x * frcp_(1.0f + __expf(-x)); }
; __device__ __forceinline__ float softplusf_(float x) { return x > 20.f ? x : log1pf(__expf(x)); }
; __device__ __forceinline__ void ssd_sample_step(const bf16* proj, const float* conv_w, const float* conv_b, const float* dt_bias, const float* a_log, const float* d_skip, const float* ssm_norm, ...
;     ...
;     {
;         const int chx = tid < 256 ? (grp * 256 + tid) : (tid < 384 ? (2048 + grp * 128 + (tid - 256)) : (3072 + grp * 128 + (tid - 384)));
;         const float* ci = conv_in + (size_t)b * 3 * 4096; const float r0 = ci[chx], r1 = ci[4096 + chx], r2 = ci[8192 + chx];
;         const float cur = bf2f(proj[row * LDP + PC_XBC + chx]);
;         const float cw0 = conv_w[chx], cw1 = conv_w[4096 + chx], cw2 = conv_w[8192 + chx], cw3 = conv_w[12288 + chx], cbb = conv_b[chx];
;         float dtr = 0.f, dtbv = 0.f, alg = 0.f; if (tid < 4) { const int head = grp * 4 + tid; dtr = bf2f(proj[row * LDP + PC_DT + head]); dtbv = dt_bias[head]; alg = a_log[head]; }
;         const float a = cbb + cw0 * r0 + cw1 * r1 + cw2 * r2 + cw3 * cur;
;         const float v = siluf_(a);
;         if (tid < 256) sx[tid] = v; else if (tid < 384) sB[tid - 256] = v; else sC[tid - 384] = v;
;         float* co = conv_out + (size_t)b * 3 * 4096; co[chx] = r1; co[4096 + chx] = r2; co[8192 + chx] = cur;
;         if (tid < 4) { const float dv = softplusf_(dtr + dtbv); sdt[tid] = dv; sdec[tid] = __expf(dv * (-__expf(alg))); } }
.LBB0_445:
	s_or_saveexec_b64 s[2:3], s[2:3]
	v_lshl_add_u32 v80, s50, 8, v8
	s_xor_b64 exec, exec, s[2:3]
	v_mov_b32_e32 v68, v80
	s_or_b64 exec, exec, s[2:3]
	s_ashr_i32 s58, s59, 3
	s_ashr_i32 s3, s58, 31
	s_add_u32 s2, s58, 0x4000
	s_mul_hi_i32 s9, s58, 0x3000
	s_mul_i32 s8, s58, 0x3000
	s_addc_u32 s3, s3, 0
	s_lshl_b64 s[12:13], s[8:9], 2
	s_add_u32 s8, s28, s12
	v_ashrrev_i32_e32 v69, 31, v68
	s_addc_u32 s9, s29, s13
	v_lshlrev_b64 v[72:73], 2, v[68:69]
	v_lshl_add_u64 v[74:75], s[8:9], 0, v[72:73]
	s_movk_i32 s14, 0x4000
	v_add_co_u32_e32 v70, vcc, s14, v74
	s_mov_b32 s8, 0x8000
	s_nop 0
	v_addc_co_u32_e32 v71, vcc, 0, v75, vcc
	s_mul_i32 s9, s2, 0x6200
	global_load_dword v10, v[74:75], off
	s_add_u32 s10, s78, s9
	global_load_dword v70, v[70:71], off
	v_add_co_u32_e32 v74, vcc, s8, v74
	s_mul_hi_i32 s8, s2, 0x6200
	s_nop 0
	v_addc_co_u32_e32 v75, vcc, 0, v75, vcc
	s_addc_u32 s11, s79, s8
	global_load_dword v71, v[74:75], off
	v_lshl_add_u64 v[74:75], v[68:69], 1, s[10:11]
	s_movk_i32 s8, 0x3000
	v_add_co_u32_e32 v74, vcc, s8, v74
	v_lshl_add_u64 v[78:79], s[30:31], 0, v[72:73]
	s_nop 0
	v_addc_co_u32_e32 v75, vcc, 0, v75, vcc
	v_add_co_u32_e32 v76, vcc, s14, v78
	global_load_ushort v74, v[74:75], off
	s_nop 0
	v_addc_co_u32_e32 v77, vcc, 0, v79, vcc
	v_add_co_u32_e32 v82, vcc, 0x8000, v78
	global_load_dword v75, v[78:79], off
	s_nop 0
	v_addc_co_u32_e32 v83, vcc, 0, v79, vcc
	global_load_dword v76, v[76:77], off
	v_add_co_u32_e32 v78, vcc, 0xc000, v78
	v_lshl_add_u64 v[72:73], s[34:35], 0, v[72:73]
	s_nop 0
	v_addc_co_u32_e32 v79, vcc, 0, v79, vcc
	global_load_dword v77, v[82:83], off
	v_cmp_gt_i32_e64 s[8:9], 4, v8
	global_load_dword v79, v[78:79], off
	v_mov_b32_e32 v9, 0
	global_load_dword v78, v[72:73], off
	v_mov_b32_e32 v73, 0
	v_mov_b32_e32 v72, 0
	s_and_saveexec_b64 s[14:15], s[8:9]
	s_cbranch_execz .LBB0_449
	v_lshl_add_u32 v82, s50, 2, v8
	v_ashrrev_i32_e32 v83, 31, v82
	v_lshl_add_u64 v[72:73], v[82:83], 1, s[10:11]
	v_add_co_u32_e32 v72, vcc, 0x6000, v72
	v_lshlrev_b64 v[82:83], 2, v[82:83]
	s_nop 0
	v_addc_co_u32_e32 v73, vcc, 0, v73, vcc
	global_load_ushort v9, v[72:73], off
	v_lshl_add_u64 v[84:85], s[36:37], 0, v[82:83]
	v_lshl_add_u64 v[82:83], s[60:61], 0, v[82:83]
	global_load_dword v73, v[84:85], off
	global_load_dword v84, v[82:83], off
	s_waitcnt vmcnt(0) lgkmcnt(0)
	v_lshlrev_b32_e32 v72, 16, v9
	s_nop 0
	v_mul_f32_e32 v9, 0x3fb8aa3b, v84

; __device__ __forceinline__ float bf2f(bf16 v) { return __uint_as_float(((unsigned)v) << 16); }
; __device__ __forceinline__ float sigmoidf_(float x) { return frcp_(1.0f + __expf(-x)); }
; __device__ __forceinline__ float siluf_(float x) { return x * frcp_(1.0f + __expf(-x)); }
; __host__ __device__ __forceinline__ int hg_vpos(int e) { return (e & 64) + 16 * (e & 3) + ((e & 63) >> 2); }
; __device__ __forceinline__ void hgrn_sample_step(const bf16* proj, const float* lbs_l, const float* hgn_l, const float* state_in, float* state_out, bf16* ohg, int bh, int tid, LAS unsigned char* lds,
;                                                  f32x4 (&st)[8], int bh_next) {
;     ...
;     const size_t row = (size_t)MP + b;
;     float ogv = 0.f, q_ = 0.f, f_ = 0.f, v_ = 0.f, lb_ = 0.f;
;     if (tid < 128) { const bf16* pr = proj + row * LDP + h * 128; q_ = bf2f(pr[PC_Q + tid]); f_ = bf2f(pr[PC_F + tid]); lb_ = lbs_l[h * 128 + tid]; v_ = bf2f(pr[PC_I + hg_vpos(tid)]); ogv = bf2f(pr[PC_OG + tid]); }
;     if (tid < 128) { const float fg = lb_ + (1.f - lb_) * sigmoidf_(f_);
;         sq[tid] = siluf_(q_) * 0.08838834764831845f; sg[tid] = fg; sk[tid] = 1.f - fg; sv[tid] = v_; }
.LBB0_552:
	s_ashr_i32 s6, s18, 3
	v_mov_b32_e32 v8, v138
	s_add_i32 s10, s6, 0x4000
	s_movk_i32 s6, 0x80
	s_and_b32 s16, s18, 7
	s_ashr_i32 s11, s10, 31
	v_cmp_gt_i32_e64 s[6:7], s6, v8
	s_waitcnt vmcnt(0) lgkmcnt(0)
	v_bfrev_b32_e32 v38, 1
	v_mov_b32_e32 v36, 0
	v_ashrrev_i32_e32 v9, 31, v8
	v_mov_b32_e32 v68, 0
	v_mov_b32_e32 v10, 0
	v_mov_b32_e32 v37, 0
	s_and_saveexec_b64 s[8:9], s[6:7]
	s_cbranch_execz .LBB0_554
	s_mul_i32 s13, s10, 0x6200
	s_mul_hi_i32 s12, s10, 0x6200
	s_add_u32 s13, s78, s13
	s_addc_u32 s14, s79, s12
	s_lshl_b32 s12, s16, 8
	s_add_u32 s12, s13, s12
	s_addc_u32 s13, s14, 0
	v_lshl_add_u64 v[38:39], v[8:9], 1, s[12:13]
	global_load_ushort v10, v[38:39], off offset:2048
	v_lshl_add_u32 v36, s16, 7, v8
	v_ashrrev_i32_e32 v37, 31, v36
	v_lshl_add_u64 v[36:37], v[36:37], 2, s[96:97]
	global_load_dword v36, v[36:37], off
	v_lshlrev_b32_e32 v37, 4, v8
	v_and_b32_e32 v37, 48, v37
	v_bfe_u32 v40, v8, 2, 4
	s_waitcnt vmcnt(0) lgkmcnt(0)
	v_lshlrev_b32_e32 v42, 16, v10
	v_and_b32_e32 v10, 64, v8
	v_or3_b32 v10, v37, v10, v40
	v_lshlrev_b32_e32 v10, 1, v10
	v_lshl_add_u64 v[40:41], s[12:13], 0, v[10:11]
	s_movk_i32 s12, 0x1000
	v_add_co_u32_e32 v40, vcc, s12, v40
	s_nop 1
	v_addc_co_u32_e32 v41, vcc, 0, v41, vcc
	global_load_ushort v10, v[40:41], off
	global_load_ushort v37, v[38:39], off
	v_add_co_u32_e32 v38, vcc, 0x1000, v38
	s_nop 1
	v_addc_co_u32_e32 v39, vcc, 0, v39, vcc
	global_load_ushort v38, v[38:39], off offset:2048
	s_waitcnt vmcnt(0) lgkmcnt(0)
	v_lshlrev_b32_e32 v10, 16, v10
	v_lshlrev_b32_e32 v37, 16, v37
	v_lshlrev_b32_e32 v68, 16, v38
	v_mul_f32_e32 v38, 0xbfb8aa3b, v42

; __device__ __forceinline__ float bf2f(bf16 v) { return __uint_as_float(((unsigned)v) << 16); }
; __device__ __forceinline__ float softplusf_(float x) { return x > 20.f ? x : log1pf(__expf(x)); }
; __device__ __forceinline__ void ssd_sample_step(const bf16* proj, const float* conv_w, const float* conv_b, const float* dt_bias, const float* a_log, const float* d_skip, const float* ssm_norm, ...
;     ...
;     {
;         const int chx = tid < 256 ? (grp * 256 + tid) : (tid < 384 ? (2048 + grp * 128 + (tid - 256)) : (3072 + grp * 128 + (tid - 384)));
;         const float* ci = conv_in + (size_t)b * 3 * 4096; const float r0 = ci[chx], r1 = ci[4096 + chx], r2 = ci[8192 + chx];
;         const float cur = bf2f(proj[row * LDP + PC_XBC + chx]);
;         const float cw0 = conv_w[chx], cw1 = conv_w[4096 + chx], cw2 = conv_w[8192 + chx], cw3 = conv_w[12288 + chx], cbb = conv_b[chx];
;         float dtr = 0.f, dtbv = 0.f, alg = 0.f; if (tid < 4) { const int head = grp * 4 + tid; dtr = bf2f(proj[row * LDP + PC_DT + head]); dtbv = dt_bias[head]; alg = a_log[head]; }
;     ...
;         if (tid < 4) { const float dv = softplusf_(dtr + dtbv); sdt[tid] = dv; sdec[tid] = __expf(dv * (-__expf(alg))); } }
.LBB0_589:
	s_or_saveexec_b64 s[2:3], s[2:3]
	v_lshl_add_u32 v80, s28, 8, v8
	s_xor_b64 exec, exec, s[2:3]
	v_mov_b32_e32 v68, v80
	s_or_b64 exec, exec, s[2:3]
	s_ashr_i32 s50, s51, 3
	s_ashr_i32 s3, s50, 31
	s_add_u32 s2, s50, 0x4000
	s_mul_hi_i32 s9, s50, 0x3000
	s_mul_i32 s8, s50, 0x3000
	s_addc_u32 s3, s3, 0
	s_lshl_b64 s[12:13], s[8:9], 2
	s_add_u32 s8, s22, s12
	v_ashrrev_i32_e32 v69, 31, v68
	s_addc_u32 s9, s23, s13
	v_lshlrev_b64 v[72:73], 2, v[68:69]
	v_lshl_add_u64 v[74:75], s[8:9], 0, v[72:73]
	s_movk_i32 s14, 0x4000
	v_add_co_u32_e32 v70, vcc, s14, v74
	s_mov_b32 s8, 0x8000
	s_nop 0
	v_addc_co_u32_e32 v71, vcc, 0, v75, vcc
	s_mul_i32 s9, s2, 0x6200
	global_load_dword v10, v[74:75], off
	s_add_u32 s10, s78, s9
	global_load_dword v70, v[70:71], off
	v_add_co_u32_e32 v74, vcc, s8, v74
	s_mul_hi_i32 s8, s2, 0x6200
	s_nop 0
	v_addc_co_u32_e32 v75, vcc, 0, v75, vcc
	s_addc_u32 s11, s79, s8
	global_load_dword v71, v[74:75], off
	v_lshl_add_u64 v[74:75], v[68:69], 1, s[10:11]
	s_movk_i32 s8, 0x3000
	v_add_co_u32_e32 v74, vcc, s8, v74
	v_lshl_add_u64 v[78:79], s[30:31], 0, v[72:73]
	s_nop 0
	v_addc_co_u32_e32 v75, vcc, 0, v75, vcc
	v_add_co_u32_e32 v76, vcc, s14, v78
	global_load_ushort v74, v[74:75], off
	s_nop 0
	v_addc_co_u32_e32 v77, vcc, 0, v79, vcc
	v_add_co_u32_e32 v82, vcc, 0x8000, v78
	global_load_dword v75, v[78:79], off
	s_nop 0
	v_addc_co_u32_e32 v83, vcc, 0, v79, vcc
	global_load_dword v76, v[76:77], off
	v_add_co_u32_e32 v78, vcc, 0xc000, v78
	v_lshl_add_u64 v[72:73], s[34:35], 0, v[72:73]
	s_nop 0
	v_addc_co_u32_e32 v79, vcc, 0, v79, vcc
	global_load_dword v77, v[82:83], off
	v_cmp_gt_i32_e64 s[8:9], 4, v8
	global_load_dword v79, v[78:79], off
	v_mov_b32_e32 v9, 0
	global_load_dword v78, v[72:73], off
	v_mov_b32_e32 v73, 0
	v_mov_b32_e32 v72, 0
	s_and_saveexec_b64 s[14:15], s[8:9]
	s_cbranch_execz .LBB0_593
	v_lshl_add_u32 v82, s28, 2, v8
	v_ashrrev_i32_e32 v83, 31, v82
	v_lshl_add_u64 v[72:73], v[82:83], 1, s[10:11]
	v_add_co_u32_e32 v72, vcc, 0x6000, v72
	v_lshlrev_b64 v[82:83], 2, v[82:83]
	s_nop 0
	v_addc_co_u32_e32 v73, vcc, 0, v73, vcc
	global_load_ushort v9, v[72:73], off
	v_lshl_add_u64 v[84:85], s[36:37], 0, v[82:83]
	v_lshl_add_u64 v[82:83], s[60:61], 0, v[82:83]
	global_load_dword v73, v[84:85], off
	global_load_dword v84, v[82:83], off
	s_waitcnt vmcnt(0) lgkmcnt(0)
	v_lshlrev_b32_e32 v72, 16, v9
	s_nop 0
	v_mul_f32_e32 v9, 0x3fb8aa3b, v84

; #define LAUNDER_PTR(p) do {} while (0)
; #define LAUNDER_PTR(p) asm volatile("" : "+v"(p))
; __device__ __forceinline__ void ssd_pass2(const RecurBufs& rb, const float* d_skip, const float* ssm_norm, float* state_out_l, int u, int tid, LAS unsigned char* lds) {
;     ...
;     for (int ch = 0; ch < NCH; ++ch) {
;         const size_t row0 = rowS + ch * RC;
;         {   v4u raw[8];
;             {   const bf16* gp = rb.xbcc + (row0 + rr) * 4096 + gcol;
; #pragma unroll
;                 for (int i = 0; i < 8; ++i) { LAUNDER_PTR(gp); raw[i] = *(const v4u*)gp; gp += 8 * 4096; } }
;             if (tid < 256) { sDt[tid] = rb.dtv[(row0 + (tid >> 2)) * 32 + grp * 4 + (tid & 3)]; sCum[tid] = rb.cum[(row0 + (tid >> 2)) * 32 + grp * 4 + (tid & 3)]; }
.LBB0_866:
	s_lshl_b32 s2, s62, 6
	s_add_u32 s60, s36, s2
	s_addc_u32 s61, s37, 0
	v_lshl_add_u64 v[12:13], s[60:61], 0, v[104:105]
	v_lshlrev_b64 v[12:13], 13, v[12:13]
	v_lshl_add_u64 v[12:13], v[114:115], 0, v[12:13]
	global_load_dwordx4 v[70:73], v[12:13], off
	v_lshl_add_u64 v[12:13], v[12:13], 0, s[42:43]
	global_load_dwordx4 v[74:77], v[12:13], off
	v_lshl_add_u64 v[12:13], v[12:13], 0, s[42:43]
	global_load_dwordx4 v[78:81], v[12:13], off
	v_lshl_add_u64 v[12:13], v[12:13], 0, s[42:43]
	global_load_dwordx4 v[82:85], v[12:13], off
	v_lshl_add_u64 v[12:13], v[12:13], 0, s[42:43]
	global_load_dwordx4 v[86:89], v[12:13], off
	v_lshl_add_u64 v[12:13], v[12:13], 0, s[42:43]
	global_load_dwordx4 v[90:93], v[12:13], off
	v_lshl_add_u64 v[12:13], v[12:13], 0, s[42:43]
	global_load_dwordx4 v[94:97], v[12:13], off
	v_lshl_add_u64 v[12:13], v[12:13], 0, s[42:43]
	global_load_dwordx4 v[98:101], v[12:13], off
	s_and_saveexec_b64 s[2:3], s[4:5]
	s_cbranch_execz .LBB0_868
	v_lshl_add_u64 v[12:13], s[60:61], 0, v[106:107]
	v_lshlrev_b64 v[12:13], 7, v[12:13]
	v_lshl_or_b32 v12, v108, 2, v12
	v_lshl_add_u64 v[122:123], s[22:23], 0, v[12:13]
	global_load_dword v10, v[122:123], off
	v_lshl_add_u64 v[12:13], s[24:25], 0, v[12:13]
	global_load_dword v179, v[12:13], off
	s_waitcnt vmcnt(0) lgkmcnt(0)
	ds_write_b32 v128, v10
	s_nop 0
	ds_write_b32 v129, v179
